# in_proj: nt stores only for the outputs consumed late (GLA q and silu gates, read in GLA pass 1), keeping the cache for the attention / GLA pass-0 operands
# speedup vs baseline: 1.0040x; 1.0040x over previous
.LBB0_407:
	s_cmp_gt_u32 s36, 6
	s_cselect_b32 s98, 1, 0
	s_cmp_eq_u32 s36, 3
	s_cselect_b32 s98, 1, s98
	v_add_u32_e32 v167, s19, v180
	ds_read_b32 v128, v167
	s_cmp_gt_u32 s36, 6
	s_cselect_b64 s[38:39], -1, 0
	s_cmp_lt_u32 s36, 7
	s_waitcnt lgkmcnt(0)
	v_mul_f32_e32 v130, s21, v128
	v_pk_mul_f32 v[134:135], v[126:127], v[130:131] op_sel_hi:[1,0]
	v_pk_mul_f32 v[136:137], v[124:125], v[130:131] op_sel_hi:[1,0]
	v_pk_mul_f32 v[138:139], v[118:119], v[130:131] op_sel_hi:[1,0]
	v_pk_mul_f32 v[140:141], v[116:117], v[130:131] op_sel_hi:[1,0]
	s_cbranch_scc1 .LBB0_409
	v_mul_f32_e32 v133, 0xbfb8aa3b, v134
	v_mul_f32_e32 v129, 0xbfb8aa3b, v140
	v_exp_f32_e32 v133, v133
	v_mul_f32_e32 v150, 0xbfb8aa3b, v138
	v_mul_f32_e32 v131, 0xbfb8aa3b, v137
	v_exp_f32_e32 v129, v129
	v_exp_f32_e32 v150, v150
	v_exp_f32_e32 v131, v131
	v_add_f32_e32 v133, 1.0, v133
	v_add_f32_e32 v129, 1.0, v129
	v_rcp_f32_e32 v168, v133
	v_add_f32_e32 v133, 1.0, v150
	v_mul_f32_e32 v150, 0xbfb8aa3b, v135
	v_mul_f32_e32 v128, 0xbfb8aa3b, v136
	v_rcp_f32_e32 v132, v129
	v_add_f32_e32 v129, 1.0, v131
	v_mul_f32_e32 v131, 0xbfb8aa3b, v141
	v_exp_f32_e32 v150, v150
	v_mul_f32_e32 v169, 0xbfb8aa3b, v139
	v_exp_f32_e32 v128, v128
	v_exp_f32_e32 v131, v131
	v_exp_f32_e32 v171, v169
	v_rcp_f32_e32 v170, v133
	v_add_f32_e32 v133, 1.0, v150
	v_add_f32_e32 v128, 1.0, v128
	v_add_f32_e32 v131, 1.0, v131
	v_rcp_f32_e32 v169, v133
	v_add_f32_e32 v133, 1.0, v171
	v_rcp_f32_e32 v128, v128
	v_rcp_f32_e32 v129, v129
	v_rcp_f32_e32 v171, v133
	v_rcp_f32_e32 v133, v131
	v_pk_mul_f32 v[134:135], v[134:135], v[168:169]
	v_pk_mul_f32 v[136:137], v[136:137], v[128:129]
	v_pk_mul_f32 v[138:139], v[138:139], v[170:171]
	v_pk_mul_f32 v[140:141], v[140:141], v[132:133]
.LBB0_409:
	s_add_u32 s6, s6, s65
	s_addc_u32 s7, s7, 0
	v_lshlrev_b32_e32 v150, 1, v152
	v_mov_b32_e32 v131, v130
	v_lshl_add_u64 v[128:129], s[6:7], 0, v[150:151]
	v_mad_i64_i32 v[132:133], s[6:7], s8, v166, 0
	v_cvt_pk_bf16_f32 v168, v136, v137
	v_cvt_pk_bf16_f32 v170, v140, v141
	v_mov_b32_e32 v136, v130
	v_mov_b32_e32 v137, v130
	v_cndmask_b32_e64 v140, 0, 1, s[38:39]
	v_lshl_add_u64 v[132:133], v[132:133], 1, v[128:129]
	v_cvt_pk_bf16_f32 v169, v134, v135
	v_cvt_pk_bf16_f32 v171, v138, v139
	v_pk_mul_f32 v[134:135], v[122:123], v[136:137]
	v_pk_mul_f32 v[138:139], v[120:121], v[130:131]
	v_pk_mul_f32 v[136:137], v[114:115], v[136:137]
	v_cmp_ne_u32_e64 s[6:7], 1, v140
	s_andn2_b64 vcc, exec, s[38:39]
	v_pk_mul_f32 v[130:131], v[112:113], v[130:131]
	s_cmp_lg_u32 s98, 0
	s_cbranch_scc1 .Lnt_1
	global_store_dwordx4 v[132:133], v[168:171], off
	s_branch .Lntj_1
.Lnt_1:
	global_store_dwordx4 v[132:133], v[168:171], off nt
.Lntj_1:
	s_cbranch_vccnz .LBB0_411
	s_nop 0
	v_mul_f32_e32 v169, 0xbfb8aa3b, v134
	v_mul_f32_e32 v141, 0xbfb8aa3b, v130
	v_exp_f32_e32 v169, v169
	v_mul_f32_e32 v170, 0xbfb8aa3b, v136
	v_mul_f32_e32 v150, 0xbfb8aa3b, v139
	v_exp_f32_e32 v141, v141
	v_exp_f32_e32 v171, v170
	v_exp_f32_e32 v150, v150
	v_add_f32_e32 v169, 1.0, v169
	v_add_f32_e32 v141, 1.0, v141
	v_rcp_f32_e32 v170, v169
	v_add_f32_e32 v169, 1.0, v171
	v_mul_f32_e32 v171, 0xbfb8aa3b, v135
	v_mul_f32_e32 v140, 0xbfb8aa3b, v138
	v_rcp_f32_e32 v168, v141
	v_add_f32_e32 v141, 1.0, v150
	v_mul_f32_e32 v150, 0xbfb8aa3b, v131
	v_exp_f32_e32 v171, v171
	v_mul_f32_e32 v172, 0xbfb8aa3b, v137
	v_exp_f32_e32 v140, v140
	v_exp_f32_e32 v150, v150
	v_exp_f32_e32 v173, v172
	v_rcp_f32_e32 v172, v169
	v_add_f32_e32 v169, 1.0, v171
	v_add_f32_e32 v140, 1.0, v140
	v_add_f32_e32 v150, 1.0, v150
	v_rcp_f32_e32 v171, v169
	v_add_f32_e32 v169, 1.0, v173
	v_rcp_f32_e32 v140, v140
	v_rcp_f32_e32 v141, v141
	v_rcp_f32_e32 v173, v169
	v_rcp_f32_e32 v169, v150
	v_pk_mul_f32 v[134:135], v[134:135], v[170:171]
	v_pk_mul_f32 v[138:139], v[138:139], v[140:141]
	v_pk_mul_f32 v[136:137], v[136:137], v[172:173]
	v_pk_mul_f32 v[130:131], v[130:131], v[168:169]
.LBB0_411:
	ds_read_b32 v150, v167 offset:64
	v_cvt_pk_bf16_f32 v138, v138, v139
	v_cvt_pk_bf16_f32 v139, v134, v135
	v_cvt_pk_bf16_f32 v140, v130, v131
	v_cvt_pk_bf16_f32 v141, v136, v137
	s_waitcnt lgkmcnt(0)
	v_mul_f32_e32 v130, s21, v150
	s_cmp_lg_u32 s98, 0
	s_cbranch_scc1 .Lnt_2
	global_store_dwordx4 v[132:133], v[138:141], off offset:256
	s_branch .Lntj_2
.Lnt_2:
	global_store_dwordx4 v[132:133], v[138:141], off offset:256 nt
.Lntj_2:
	v_pk_mul_f32 v[134:135], v[110:111], v[130:131] op_sel_hi:[1,0]
	v_pk_mul_f32 v[136:137], v[108:109], v[130:131] op_sel_hi:[1,0]
	v_pk_mul_f32 v[138:139], v[102:103], v[130:131] op_sel_hi:[1,0]
	s_and_b64 vcc, exec, s[6:7]
	v_pk_mul_f32 v[140:141], v[100:101], v[130:131] op_sel_hi:[1,0]
	s_cbranch_vccnz .LBB0_413
	v_mul_f32_e32 v131, 0xbfb8aa3b, v136
	v_exp_f32_e32 v131, v131
	v_mul_f32_e32 v132, 0xbfb8aa3b, v140
	v_exp_f32_e32 v150, v132
	v_mul_f32_e32 v133, 0xbfb8aa3b, v137
	v_add_f32_e32 v131, 1.0, v131
	v_rcp_f32_e32 v132, v131
	v_add_f32_e32 v131, 1.0, v150
	v_mul_f32_e32 v150, 0xbfb8aa3b, v134
	v_exp_f32_e32 v150, v150
	v_mul_f32_e32 v169, 0xbfb8aa3b, v138
	v_exp_f32_e32 v133, v133
	v_exp_f32_e32 v169, v169
	v_add_f32_e32 v150, 1.0, v150
	v_rcp_f32_e32 v168, v131
	v_add_f32_e32 v131, 1.0, v133
	v_rcp_f32_e32 v170, v150
	v_add_f32_e32 v150, 1.0, v169
	v_mul_f32_e32 v169, 0xbfb8aa3b, v135
	v_rcp_f32_e32 v133, v131
	v_mul_f32_e32 v131, 0xbfb8aa3b, v141
	v_exp_f32_e32 v169, v169
	v_mul_f32_e32 v171, 0xbfb8aa3b, v139
	v_exp_f32_e32 v131, v131
	v_exp_f32_e32 v173, v171
	v_rcp_f32_e32 v172, v150
	v_add_f32_e32 v150, 1.0, v169
	v_add_f32_e32 v131, 1.0, v131
	v_rcp_f32_e32 v171, v150
	v_add_f32_e32 v150, 1.0, v173
	v_rcp_f32_e32 v173, v150
	v_rcp_f32_e32 v169, v131
	v_pk_mul_f32 v[134:135], v[134:135], v[170:171]
	v_pk_mul_f32 v[136:137], v[136:137], v[132:133]
	v_pk_mul_f32 v[138:139], v[138:139], v[172:173]
	v_pk_mul_f32 v[140:141], v[140:141], v[168:169]
.LBB0_413:
	v_or_b32_e32 v132, 16, v166
	v_mov_b32_e32 v131, v130
	v_mad_i64_i32 v[132:133], s[38:39], s8, v132, 0
	v_cvt_pk_bf16_f32 v168, v136, v137
	v_mov_b32_e32 v136, v130
	v_mov_b32_e32 v137, v130
	v_lshl_add_u64 v[132:133], v[132:133], 1, v[128:129]
	v_cvt_pk_bf16_f32 v169, v134, v135
	v_cvt_pk_bf16_f32 v170, v140, v141
	v_cvt_pk_bf16_f32 v171, v138, v139
	v_pk_mul_f32 v[134:135], v[106:107], v[136:137]
	v_pk_mul_f32 v[138:139], v[104:105], v[130:131]
	v_pk_mul_f32 v[136:137], v[98:99], v[136:137]
	s_and_b64 vcc, exec, s[6:7]
	v_pk_mul_f32 v[130:131], v[96:97], v[130:131]
	s_cmp_lg_u32 s98, 0
	s_cbranch_scc1 .Lnt_3
	global_store_dwordx4 v[132:133], v[168:171], off
	s_branch .Lntj_3

.LBB0_415:
	ds_read_b32 v150, v167 offset:128
	v_cvt_pk_bf16_f32 v138, v138, v139
	v_cvt_pk_bf16_f32 v139, v134, v135
	v_cvt_pk_bf16_f32 v140, v130, v131
	v_cvt_pk_bf16_f32 v141, v136, v137
	s_waitcnt lgkmcnt(0)
	v_mul_f32_e32 v130, s21, v150
	s_cmp_lg_u32 s98, 0
	s_cbranch_scc1 .Lnt_4
	global_store_dwordx4 v[132:133], v[138:141], off offset:256
	s_branch .Lntj_4

.Lntj_4:
	v_pk_mul_f32 v[134:135], v[94:95], v[130:131] op_sel_hi:[1,0]
	v_pk_mul_f32 v[136:137], v[92:93], v[130:131] op_sel_hi:[1,0]
	v_pk_mul_f32 v[138:139], v[86:87], v[130:131] op_sel_hi:[1,0]
	s_and_b64 vcc, exec, s[6:7]
	v_pk_mul_f32 v[140:141], v[84:85], v[130:131] op_sel_hi:[1,0]
	s_cbranch_vccnz .LBB0_417
	v_mul_f32_e32 v131, 0xbfb8aa3b, v136
	v_exp_f32_e32 v131, v131
	v_mul_f32_e32 v132, 0xbfb8aa3b, v140
	v_exp_f32_e32 v150, v132
	v_mul_f32_e32 v133, 0xbfb8aa3b, v137
	v_add_f32_e32 v131, 1.0, v131
	v_rcp_f32_e32 v132, v131
	v_add_f32_e32 v131, 1.0, v150
	v_mul_f32_e32 v150, 0xbfb8aa3b, v134
	v_exp_f32_e32 v150, v150
	v_mul_f32_e32 v169, 0xbfb8aa3b, v138
	v_exp_f32_e32 v133, v133
	v_exp_f32_e32 v169, v169
	v_add_f32_e32 v150, 1.0, v150
	v_rcp_f32_e32 v168, v131
	v_add_f32_e32 v131, 1.0, v133
	v_rcp_f32_e32 v170, v150
	v_add_f32_e32 v150, 1.0, v169
	v_mul_f32_e32 v169, 0xbfb8aa3b, v135
	v_rcp_f32_e32 v133, v131
	v_mul_f32_e32 v131, 0xbfb8aa3b, v141
	v_exp_f32_e32 v169, v169
	v_mul_f32_e32 v171, 0xbfb8aa3b, v139
	v_exp_f32_e32 v131, v131
	v_exp_f32_e32 v173, v171
	v_rcp_f32_e32 v172, v150
	v_add_f32_e32 v150, 1.0, v169
	v_add_f32_e32 v131, 1.0, v131
	v_rcp_f32_e32 v171, v150
	v_add_f32_e32 v150, 1.0, v173
	v_rcp_f32_e32 v173, v150
	v_rcp_f32_e32 v169, v131
	v_pk_mul_f32 v[134:135], v[134:135], v[170:171]
	v_pk_mul_f32 v[136:137], v[136:137], v[132:133]
	v_pk_mul_f32 v[138:139], v[138:139], v[172:173]
	v_pk_mul_f32 v[140:141], v[140:141], v[168:169]
.LBB0_417:
	v_or_b32_e32 v132, 32, v166
	v_mov_b32_e32 v131, v130
	v_mad_i64_i32 v[132:133], s[38:39], s8, v132, 0
	v_cvt_pk_bf16_f32 v168, v136, v137
	v_mov_b32_e32 v136, v130
	v_mov_b32_e32 v137, v130
	v_lshl_add_u64 v[132:133], v[132:133], 1, v[128:129]
	v_cvt_pk_bf16_f32 v169, v134, v135
	v_cvt_pk_bf16_f32 v170, v140, v141
	v_cvt_pk_bf16_f32 v171, v138, v139
	v_pk_mul_f32 v[134:135], v[90:91], v[136:137]
	v_pk_mul_f32 v[138:139], v[88:89], v[130:131]
	v_pk_mul_f32 v[136:137], v[82:83], v[136:137]
	s_and_b64 vcc, exec, s[6:7]
	v_pk_mul_f32 v[130:131], v[80:81], v[130:131]
	s_cmp_lg_u32 s98, 0
	s_cbranch_scc1 .Lnt_5
	global_store_dwordx4 v[132:133], v[168:171], off
	s_branch .Lntj_5

.LBB0_419:
	ds_read_b32 v150, v167 offset:192
	v_cvt_pk_bf16_f32 v138, v138, v139
	v_cvt_pk_bf16_f32 v139, v134, v135
	v_cvt_pk_bf16_f32 v140, v130, v131
	v_cvt_pk_bf16_f32 v141, v136, v137
	s_waitcnt lgkmcnt(0)
	v_mul_f32_e32 v130, s21, v150
	s_cmp_lg_u32 s98, 0
	s_cbranch_scc1 .Lnt_6
	global_store_dwordx4 v[132:133], v[138:141], off offset:256
	s_branch .Lntj_6

.Lntj_6:
	v_pk_mul_f32 v[134:135], v[78:79], v[130:131] op_sel_hi:[1,0]
	v_pk_mul_f32 v[136:137], v[76:77], v[130:131] op_sel_hi:[1,0]
	v_pk_mul_f32 v[138:139], v[70:71], v[130:131] op_sel_hi:[1,0]
	s_and_b64 vcc, exec, s[6:7]
	v_pk_mul_f32 v[140:141], v[68:69], v[130:131] op_sel_hi:[1,0]
	s_cbranch_vccnz .LBB0_421
	v_mul_f32_e32 v131, 0xbfb8aa3b, v136
	v_exp_f32_e32 v131, v131
	v_mul_f32_e32 v132, 0xbfb8aa3b, v140
	v_exp_f32_e32 v150, v132
	v_mul_f32_e32 v133, 0xbfb8aa3b, v137
	v_add_f32_e32 v131, 1.0, v131
	v_rcp_f32_e32 v132, v131
	v_add_f32_e32 v131, 1.0, v150
	v_mul_f32_e32 v150, 0xbfb8aa3b, v134
	v_exp_f32_e32 v150, v150
	v_mul_f32_e32 v169, 0xbfb8aa3b, v138
	v_exp_f32_e32 v133, v133
	v_exp_f32_e32 v169, v169
	v_add_f32_e32 v150, 1.0, v150
	v_rcp_f32_e32 v168, v131
	v_add_f32_e32 v131, 1.0, v133
	v_rcp_f32_e32 v170, v150
	v_add_f32_e32 v150, 1.0, v169
	v_mul_f32_e32 v169, 0xbfb8aa3b, v135
	v_rcp_f32_e32 v133, v131
	v_mul_f32_e32 v131, 0xbfb8aa3b, v141
	v_exp_f32_e32 v169, v169
	v_mul_f32_e32 v171, 0xbfb8aa3b, v139
	v_exp_f32_e32 v131, v131
	v_exp_f32_e32 v173, v171
	v_rcp_f32_e32 v172, v150
	v_add_f32_e32 v150, 1.0, v169
	v_add_f32_e32 v131, 1.0, v131
	v_rcp_f32_e32 v171, v150
	v_add_f32_e32 v150, 1.0, v173
	v_rcp_f32_e32 v173, v150
	v_rcp_f32_e32 v169, v131
	v_pk_mul_f32 v[134:135], v[134:135], v[170:171]
	v_pk_mul_f32 v[136:137], v[136:137], v[132:133]
	v_pk_mul_f32 v[138:139], v[138:139], v[172:173]
	v_pk_mul_f32 v[140:141], v[140:141], v[168:169]
.LBB0_421:
	v_or_b32_e32 v132, 48, v166
	v_mov_b32_e32 v131, v130
	v_mad_i64_i32 v[132:133], s[38:39], s8, v132, 0
	v_cvt_pk_bf16_f32 v168, v136, v137
	v_mov_b32_e32 v136, v130
	v_mov_b32_e32 v137, v130
	v_lshl_add_u64 v[132:133], v[132:133], 1, v[128:129]
	v_cvt_pk_bf16_f32 v169, v134, v135
	v_cvt_pk_bf16_f32 v170, v140, v141
	v_cvt_pk_bf16_f32 v171, v138, v139
	v_pk_mul_f32 v[134:135], v[74:75], v[136:137]
	v_pk_mul_f32 v[138:139], v[72:73], v[130:131]
	v_pk_mul_f32 v[136:137], v[66:67], v[136:137]
	s_and_b64 vcc, exec, s[6:7]
	v_pk_mul_f32 v[130:131], v[64:65], v[130:131]
	s_cmp_lg_u32 s98, 0
	s_cbranch_scc1 .Lnt_7
	global_store_dwordx4 v[132:133], v[168:171], off
	s_branch .Lntj_7

.LBB0_423:
	ds_read_b32 v150, v167 offset:512
	v_cvt_pk_bf16_f32 v138, v138, v139
	v_cvt_pk_bf16_f32 v139, v134, v135
	v_cvt_pk_bf16_f32 v140, v130, v131
	v_cvt_pk_bf16_f32 v141, v136, v137
	s_waitcnt lgkmcnt(0)
	v_mul_f32_e32 v130, s21, v150
	s_cmp_lg_u32 s98, 0
	s_cbranch_scc1 .Lnt_8
	global_store_dwordx4 v[132:133], v[138:141], off offset:256
	s_branch .Lntj_8

.Lntj_8:
	v_pk_mul_f32 v[134:135], v[62:63], v[130:131] op_sel_hi:[1,0]
	v_pk_mul_f32 v[136:137], v[60:61], v[130:131] op_sel_hi:[1,0]
	v_pk_mul_f32 v[138:139], v[54:55], v[130:131] op_sel_hi:[1,0]
	s_and_b64 vcc, exec, s[6:7]
	v_pk_mul_f32 v[140:141], v[52:53], v[130:131] op_sel_hi:[1,0]
	s_cbranch_vccnz .LBB0_425
	v_mul_f32_e32 v131, 0xbfb8aa3b, v136
	v_exp_f32_e32 v131, v131
	v_mul_f32_e32 v132, 0xbfb8aa3b, v140
	v_exp_f32_e32 v150, v132
	v_mul_f32_e32 v133, 0xbfb8aa3b, v137
	v_add_f32_e32 v131, 1.0, v131
	v_rcp_f32_e32 v132, v131
	v_add_f32_e32 v131, 1.0, v150
	v_mul_f32_e32 v150, 0xbfb8aa3b, v134
	v_exp_f32_e32 v150, v150
	v_mul_f32_e32 v169, 0xbfb8aa3b, v138
	v_exp_f32_e32 v133, v133
	v_exp_f32_e32 v169, v169
	v_add_f32_e32 v150, 1.0, v150
	v_rcp_f32_e32 v168, v131
	v_add_f32_e32 v131, 1.0, v133
	v_rcp_f32_e32 v170, v150
	v_add_f32_e32 v150, 1.0, v169
	v_mul_f32_e32 v169, 0xbfb8aa3b, v135
	v_rcp_f32_e32 v133, v131
	v_mul_f32_e32 v131, 0xbfb8aa3b, v141
	v_exp_f32_e32 v169, v169
	v_mul_f32_e32 v171, 0xbfb8aa3b, v139
	v_exp_f32_e32 v131, v131
	v_exp_f32_e32 v173, v171
	v_rcp_f32_e32 v172, v150
	v_add_f32_e32 v150, 1.0, v169
	v_add_f32_e32 v131, 1.0, v131
	v_rcp_f32_e32 v171, v150
	v_add_f32_e32 v150, 1.0, v173
	v_rcp_f32_e32 v173, v150
	v_rcp_f32_e32 v169, v131
	v_pk_mul_f32 v[134:135], v[134:135], v[170:171]
	v_pk_mul_f32 v[136:137], v[136:137], v[132:133]
	v_pk_mul_f32 v[138:139], v[138:139], v[172:173]
	v_pk_mul_f32 v[140:141], v[140:141], v[168:169]
.LBB0_425:
	v_add_u32_e32 v132, 0x80, v166
	v_mov_b32_e32 v131, v130
	v_mad_i64_i32 v[132:133], s[38:39], s8, v132, 0
	v_cvt_pk_bf16_f32 v168, v136, v137
	v_mov_b32_e32 v136, v130
	v_mov_b32_e32 v137, v130
	v_lshl_add_u64 v[132:133], v[132:133], 1, v[128:129]
	v_cvt_pk_bf16_f32 v169, v134, v135
	v_cvt_pk_bf16_f32 v170, v140, v141
	v_cvt_pk_bf16_f32 v171, v138, v139
	v_pk_mul_f32 v[134:135], v[58:59], v[136:137]
	v_pk_mul_f32 v[138:139], v[56:57], v[130:131]
	v_pk_mul_f32 v[136:137], v[50:51], v[136:137]
	s_and_b64 vcc, exec, s[6:7]
	v_pk_mul_f32 v[130:131], v[48:49], v[130:131]
	s_cmp_lg_u32 s98, 0
	s_cbranch_scc1 .Lnt_9
	global_store_dwordx4 v[132:133], v[168:171], off
	s_branch .Lntj_9

.LBB0_427:
	ds_read_b32 v150, v167 offset:576
	v_cvt_pk_bf16_f32 v138, v138, v139
	v_cvt_pk_bf16_f32 v139, v134, v135
	v_cvt_pk_bf16_f32 v140, v130, v131
	v_cvt_pk_bf16_f32 v141, v136, v137
	s_waitcnt lgkmcnt(0)
	v_mul_f32_e32 v130, s21, v150
	s_cmp_lg_u32 s98, 0
	s_cbranch_scc1 .Lnt_10
	global_store_dwordx4 v[132:133], v[138:141], off offset:256
	s_branch .Lntj_10

.Lntj_10:
	v_pk_mul_f32 v[134:135], v[46:47], v[130:131] op_sel_hi:[1,0]
	v_pk_mul_f32 v[136:137], v[44:45], v[130:131] op_sel_hi:[1,0]
	v_pk_mul_f32 v[138:139], v[38:39], v[130:131] op_sel_hi:[1,0]
	s_and_b64 vcc, exec, s[6:7]
	v_pk_mul_f32 v[140:141], v[36:37], v[130:131] op_sel_hi:[1,0]
	s_cbranch_vccnz .LBB0_429
	v_mul_f32_e32 v131, 0xbfb8aa3b, v136
	v_exp_f32_e32 v131, v131
	v_mul_f32_e32 v132, 0xbfb8aa3b, v140
	v_exp_f32_e32 v150, v132
	v_mul_f32_e32 v133, 0xbfb8aa3b, v137
	v_add_f32_e32 v131, 1.0, v131
	v_rcp_f32_e32 v132, v131
	v_add_f32_e32 v131, 1.0, v150
	v_mul_f32_e32 v150, 0xbfb8aa3b, v134
	v_exp_f32_e32 v150, v150
	v_mul_f32_e32 v169, 0xbfb8aa3b, v138
	v_exp_f32_e32 v133, v133
	v_exp_f32_e32 v169, v169
	v_add_f32_e32 v150, 1.0, v150
	v_rcp_f32_e32 v168, v131
	v_add_f32_e32 v131, 1.0, v133
	v_rcp_f32_e32 v170, v150
	v_add_f32_e32 v150, 1.0, v169
	v_mul_f32_e32 v169, 0xbfb8aa3b, v135
	v_rcp_f32_e32 v133, v131
	v_mul_f32_e32 v131, 0xbfb8aa3b, v141
	v_exp_f32_e32 v169, v169
	v_mul_f32_e32 v171, 0xbfb8aa3b, v139
	v_exp_f32_e32 v131, v131
	v_exp_f32_e32 v173, v171
	v_rcp_f32_e32 v172, v150
	v_add_f32_e32 v150, 1.0, v169
	v_add_f32_e32 v131, 1.0, v131
	v_rcp_f32_e32 v171, v150
	v_add_f32_e32 v150, 1.0, v173
	v_rcp_f32_e32 v173, v150
	v_rcp_f32_e32 v169, v131
	v_pk_mul_f32 v[134:135], v[134:135], v[170:171]
	v_pk_mul_f32 v[136:137], v[136:137], v[132:133]
	v_pk_mul_f32 v[138:139], v[138:139], v[172:173]
	v_pk_mul_f32 v[140:141], v[140:141], v[168:169]
.LBB0_429:
	v_add_u32_e32 v132, 0x90, v166
	v_mov_b32_e32 v131, v130
	v_mad_i64_i32 v[132:133], s[38:39], s8, v132, 0
	v_cvt_pk_bf16_f32 v168, v136, v137
	v_mov_b32_e32 v136, v130
	v_mov_b32_e32 v137, v130
	v_lshl_add_u64 v[132:133], v[132:133], 1, v[128:129]
	v_cvt_pk_bf16_f32 v169, v134, v135
	v_cvt_pk_bf16_f32 v170, v140, v141
	v_cvt_pk_bf16_f32 v171, v138, v139
	v_pk_mul_f32 v[134:135], v[42:43], v[136:137]
	v_pk_mul_f32 v[138:139], v[40:41], v[130:131]
	v_pk_mul_f32 v[136:137], v[34:35], v[136:137]
	s_and_b64 vcc, exec, s[6:7]
	v_pk_mul_f32 v[130:131], v[32:33], v[130:131]
	s_cmp_lg_u32 s98, 0
	s_cbranch_scc1 .Lnt_11
	global_store_dwordx4 v[132:133], v[168:171], off
	s_branch .Lntj_11

.LBB0_431:
	ds_read_b32 v150, v167 offset:640
	v_cvt_pk_bf16_f32 v138, v138, v139
	v_cvt_pk_bf16_f32 v139, v134, v135
	v_cvt_pk_bf16_f32 v140, v130, v131
	v_cvt_pk_bf16_f32 v141, v136, v137
	s_waitcnt lgkmcnt(0)
	v_mul_f32_e32 v130, s21, v150
	s_cmp_lg_u32 s98, 0
	s_cbranch_scc1 .Lnt_12
	global_store_dwordx4 v[132:133], v[138:141], off offset:256
	s_branch .Lntj_12

.Lntj_12:
	v_pk_mul_f32 v[134:135], v[30:31], v[130:131] op_sel_hi:[1,0]
	v_pk_mul_f32 v[136:137], v[28:29], v[130:131] op_sel_hi:[1,0]
	v_pk_mul_f32 v[138:139], v[22:23], v[130:131] op_sel_hi:[1,0]
	s_and_b64 vcc, exec, s[6:7]
	v_pk_mul_f32 v[140:141], v[20:21], v[130:131] op_sel_hi:[1,0]
	s_cbranch_vccnz .LBB0_433
	v_mul_f32_e32 v131, 0xbfb8aa3b, v136
	v_exp_f32_e32 v131, v131
	v_mul_f32_e32 v132, 0xbfb8aa3b, v140
	v_exp_f32_e32 v150, v132
	v_mul_f32_e32 v133, 0xbfb8aa3b, v137
	v_add_f32_e32 v131, 1.0, v131
	v_rcp_f32_e32 v132, v131
	v_add_f32_e32 v131, 1.0, v150
	v_mul_f32_e32 v150, 0xbfb8aa3b, v134
	v_exp_f32_e32 v150, v150
	v_mul_f32_e32 v169, 0xbfb8aa3b, v138
	v_exp_f32_e32 v133, v133
	v_exp_f32_e32 v169, v169
	v_add_f32_e32 v150, 1.0, v150
	v_rcp_f32_e32 v168, v131
	v_add_f32_e32 v131, 1.0, v133
	v_rcp_f32_e32 v170, v150
	v_add_f32_e32 v150, 1.0, v169
	v_mul_f32_e32 v169, 0xbfb8aa3b, v135
	v_rcp_f32_e32 v133, v131
	v_mul_f32_e32 v131, 0xbfb8aa3b, v141
	v_exp_f32_e32 v169, v169
	v_mul_f32_e32 v171, 0xbfb8aa3b, v139
	v_exp_f32_e32 v131, v131
	v_exp_f32_e32 v173, v171
	v_rcp_f32_e32 v172, v150
	v_add_f32_e32 v150, 1.0, v169
	v_add_f32_e32 v131, 1.0, v131
	v_rcp_f32_e32 v171, v150
	v_add_f32_e32 v150, 1.0, v173
	v_rcp_f32_e32 v173, v150
	v_rcp_f32_e32 v169, v131
	v_pk_mul_f32 v[134:135], v[134:135], v[170:171]
	v_pk_mul_f32 v[136:137], v[136:137], v[132:133]
	v_pk_mul_f32 v[138:139], v[138:139], v[172:173]
	v_pk_mul_f32 v[140:141], v[140:141], v[168:169]
.LBB0_433:
	v_add_u32_e32 v132, 0xa0, v166
	v_mov_b32_e32 v131, v130
	v_mad_i64_i32 v[132:133], s[38:39], s8, v132, 0
	v_cvt_pk_bf16_f32 v168, v136, v137
	v_mov_b32_e32 v136, v130
	v_mov_b32_e32 v137, v130
	v_lshl_add_u64 v[132:133], v[132:133], 1, v[128:129]
	v_cvt_pk_bf16_f32 v169, v134, v135
	v_cvt_pk_bf16_f32 v170, v140, v141
	v_cvt_pk_bf16_f32 v171, v138, v139
	v_pk_mul_f32 v[134:135], v[26:27], v[136:137]
	v_pk_mul_f32 v[138:139], v[24:25], v[130:131]
	v_pk_mul_f32 v[136:137], v[18:19], v[136:137]
	s_and_b64 vcc, exec, s[6:7]
	v_pk_mul_f32 v[130:131], v[16:17], v[130:131]
	s_cmp_lg_u32 s98, 0
	s_cbranch_scc1 .Lnt_13
	global_store_dwordx4 v[132:133], v[168:171], off
	s_branch .Lntj_13

.LBB0_435:
	ds_read_b32 v150, v167 offset:704
	v_cvt_pk_bf16_f32 v138, v138, v139
	v_cvt_pk_bf16_f32 v139, v134, v135
	v_cvt_pk_bf16_f32 v140, v130, v131
	v_cvt_pk_bf16_f32 v141, v136, v137
	s_waitcnt lgkmcnt(0)
	v_mul_f32_e32 v130, s21, v150
	s_cmp_lg_u32 s98, 0
	s_cbranch_scc1 .Lnt_14
	global_store_dwordx4 v[132:133], v[138:141], off offset:256
	s_branch .Lntj_14

.Lntj_14:
	v_pk_mul_f32 v[132:133], v[14:15], v[130:131] op_sel_hi:[1,0]
	v_pk_mul_f32 v[134:135], v[12:13], v[130:131] op_sel_hi:[1,0]
	v_pk_mul_f32 v[136:137], v[6:7], v[130:131] op_sel_hi:[1,0]
	s_and_b64 vcc, exec, s[6:7]
	v_pk_mul_f32 v[138:139], v[4:5], v[130:131] op_sel_hi:[1,0]
	s_cbranch_vccnz .LBB0_437
	v_mul_f32_e32 v131, 0xbfb8aa3b, v134
	v_exp_f32_e32 v131, v131
	v_mul_f32_e32 v140, 0xbfb8aa3b, v138
	v_exp_f32_e32 v150, v140
	v_mul_f32_e32 v141, 0xbfb8aa3b, v135
	v_add_f32_e32 v131, 1.0, v131
	v_rcp_f32_e32 v140, v131
	v_add_f32_e32 v131, 1.0, v150
	v_mul_f32_e32 v150, 0xbfb8aa3b, v132
	v_exp_f32_e32 v150, v150
	v_mul_f32_e32 v167, 0xbfb8aa3b, v136
	v_exp_f32_e32 v141, v141
	v_exp_f32_e32 v167, v167
	v_add_f32_e32 v150, 1.0, v150
	v_rcp_f32_e32 v168, v131
	v_add_f32_e32 v131, 1.0, v141
	v_rcp_f32_e32 v170, v150
	v_add_f32_e32 v150, 1.0, v167
	v_mul_f32_e32 v167, 0xbfb8aa3b, v133
	v_rcp_f32_e32 v141, v131
	v_mul_f32_e32 v131, 0xbfb8aa3b, v139
	v_exp_f32_e32 v167, v167
	v_mul_f32_e32 v169, 0xbfb8aa3b, v137
	v_exp_f32_e32 v131, v131
	v_exp_f32_e32 v169, v169
	v_rcp_f32_e32 v172, v150
	v_add_f32_e32 v150, 1.0, v167
	v_add_f32_e32 v131, 1.0, v131
	v_rcp_f32_e32 v171, v150
	v_add_f32_e32 v150, 1.0, v169
	v_rcp_f32_e32 v173, v150
	v_rcp_f32_e32 v169, v131
	v_pk_mul_f32 v[132:133], v[132:133], v[170:171]
	v_pk_mul_f32 v[134:135], v[134:135], v[140:141]
	v_pk_mul_f32 v[136:137], v[136:137], v[172:173]
	v_pk_mul_f32 v[138:139], v[138:139], v[168:169]
.LBB0_437:
	v_add_u32_e32 v140, 0xb0, v166
	v_mov_b32_e32 v131, v130
	v_mad_i64_i32 v[140:141], s[8:9], s8, v140, 0
	v_cvt_pk_bf16_f32 v171, v136, v137
	v_mov_b32_e32 v136, v130
	v_mov_b32_e32 v137, v130
	v_lshl_add_u64 v[128:129], v[140:141], 1, v[128:129]
	v_cvt_pk_bf16_f32 v168, v134, v135
	v_cvt_pk_bf16_f32 v169, v132, v133
	v_cvt_pk_bf16_f32 v170, v138, v139
	v_pk_mul_f32 v[132:133], v[10:11], v[136:137]
	v_pk_mul_f32 v[134:135], v[8:9], v[130:131]
	v_pk_mul_f32 v[136:137], v[2:3], v[136:137]
	s_and_b64 vcc, exec, s[6:7]
	v_pk_mul_f32 v[130:131], v[0:1], v[130:131]
	s_cmp_lg_u32 s98, 0
	s_cbranch_scc1 .Lnt_15
	global_store_dwordx4 v[128:129], v[168:171], off
	s_branch .Lntj_15
.Lnt_15:
	global_store_dwordx4 v[128:129], v[168:171], off nt
.Lntj_15:
	s_cbranch_vccnz .LBB0_439
	v_mul_f32_e32 v150, 0xbfb8aa3b, v132
	v_mul_f32_e32 v139, 0xbfb8aa3b, v130
	v_exp_f32_e32 v150, v150
	v_mul_f32_e32 v167, 0xbfb8aa3b, v136
	v_mul_f32_e32 v140, 0xbfb8aa3b, v135
	v_exp_f32_e32 v139, v139
	v_exp_f32_e32 v167, v167
	v_exp_f32_e32 v141, v140
	v_add_f32_e32 v150, 1.0, v150
	v_add_f32_e32 v139, 1.0, v139
	v_rcp_f32_e32 v168, v150
	v_add_f32_e32 v150, 1.0, v167
	v_mul_f32_e32 v167, 0xbfb8aa3b, v133
	v_mul_f32_e32 v138, 0xbfb8aa3b, v134
	v_rcp_f32_e32 v140, v139
	v_add_f32_e32 v139, 1.0, v141
	v_mul_f32_e32 v141, 0xbfb8aa3b, v131
	v_exp_f32_e32 v167, v167
	v_mul_f32_e32 v169, 0xbfb8aa3b, v137
	v_exp_f32_e32 v138, v138
	v_exp_f32_e32 v141, v141
	v_exp_f32_e32 v171, v169
	v_rcp_f32_e32 v170, v150
	v_add_f32_e32 v150, 1.0, v167
	v_add_f32_e32 v138, 1.0, v138
	v_add_f32_e32 v141, 1.0, v141
	v_rcp_f32_e32 v169, v150
	v_add_f32_e32 v150, 1.0, v171
	v_rcp_f32_e32 v138, v138
	v_rcp_f32_e32 v139, v139
	v_rcp_f32_e32 v171, v150
	v_rcp_f32_e32 v141, v141
	v_pk_mul_f32 v[132:133], v[132:133], v[168:169]
	v_pk_mul_f32 v[134:135], v[134:135], v[138:139]
	v_pk_mul_f32 v[136:137], v[136:137], v[170:171]
	v_pk_mul_f32 v[130:131], v[130:131], v[140:141]
.LBB0_439:
	v_cvt_pk_bf16_f32 v138, v134, v135
	v_cvt_pk_bf16_f32 v139, v132, v133
	v_cvt_pk_bf16_f32 v140, v130, v131
	v_cvt_pk_bf16_f32 v141, v136, v137
	s_cmp_lg_u32 s98, 0
	s_cbranch_scc1 .Lnt_16
	global_store_dwordx4 v[128:129], v[138:141], off offset:256
	s_branch .Lntj_16
.Lnt_16:
	global_store_dwordx4 v[128:129], v[138:141], off offset:256 nt
.Lntj_16:
	s_cbranch_execnz .LBB0_355
	s_branch .LBB0_374

	.amdhsa_kernel _Z9hymba_fwd6Params
		.amdhsa_group_segment_fixed_size 0
		.amdhsa_private_segment_fixed_size 0
		.amdhsa_kernarg_size 432
		.amdhsa_user_sgpr_count 2
		.amdhsa_user_sgpr_dispatch_ptr 0
		.amdhsa_user_sgpr_queue_ptr 0
		.amdhsa_user_sgpr_kernarg_segment_ptr 1
		.amdhsa_user_sgpr_dispatch_id 0
		.amdhsa_user_sgpr_kernarg_preload_length 0
		.amdhsa_user_sgpr_kernarg_preload_offset 0
		.amdhsa_user_sgpr_private_segment_size 0
		.amdhsa_uses_dynamic_stack 0
		.amdhsa_enable_private_segment 0
		.amdhsa_system_sgpr_workgroup_id_x 1
		.amdhsa_system_sgpr_workgroup_id_y 0
		.amdhsa_system_sgpr_workgroup_id_z 0
		.amdhsa_system_sgpr_workgroup_info 0
		.amdhsa_system_vgpr_workitem_id 2
		.amdhsa_next_free_vgpr 248
		.amdhsa_next_free_sgpr 99
		.amdhsa_accum_offset 248
		.amdhsa_reserve_vcc 1
		.amdhsa_float_round_mode_32 0
		.amdhsa_float_round_mode_16_64 0
		.amdhsa_float_denorm_mode_32 3
		.amdhsa_float_denorm_mode_16_64 3
		.amdhsa_dx10_clamp 1
		.amdhsa_ieee_mode 1
		.amdhsa_fp16_overflow 0
		.amdhsa_tg_split 0
		.amdhsa_exception_fp_ieee_invalid_op 0
		.amdhsa_exception_fp_denorm_src 0
		.amdhsa_exception_fp_ieee_div_zero 0
		.amdhsa_exception_fp_ieee_overflow 0
		.amdhsa_exception_fp_ieee_underflow 0
		.amdhsa_exception_fp_ieee_inexact 0
		.amdhsa_exception_int_div_zero 0
	.end_amdhsa_kernel

amdhsa.kernels:
  - .agpr_count:     0
    .args:
      - .offset:         0
        .size:           176
        .value_kind:     by_value
      - .offset:         176
        .size:           4
        .value_kind:     hidden_block_count_x
      - .offset:         180
        .size:           4
        .value_kind:     hidden_block_count_y
      - .offset:         184
        .size:           4
        .value_kind:     hidden_block_count_z
      - .offset:         188
        .size:           2
        .value_kind:     hidden_group_size_x
      - .offset:         190
        .size:           2
        .value_kind:     hidden_group_size_y
      - .offset:         192
        .size:           2
        .value_kind:     hidden_group_size_z
      - .offset:         194
        .size:           2
        .value_kind:     hidden_remainder_x
      - .offset:         196
        .size:           2
        .value_kind:     hidden_remainder_y
      - .offset:         198
        .size:           2
        .value_kind:     hidden_remainder_z
      - .offset:         216
        .size:           8
        .value_kind:     hidden_global_offset_x
      - .offset:         224
        .size:           8
        .value_kind:     hidden_global_offset_y
      - .offset:         232
        .size:           8
        .value_kind:     hidden_global_offset_z
      - .offset:         240
        .size:           2
        .value_kind:     hidden_grid_dims
      - .offset:         264
        .size:           8
        .value_kind:     hidden_multigrid_sync_arg
      - .offset:         296
        .size:           4
        .value_kind:     hidden_dynamic_lds_size
    .group_segment_fixed_size: 0
    .kernarg_segment_align: 8
    .kernarg_segment_size: 432
    .language:       OpenCL C
    .language_version:
      - 2
      - 0
    .max_flat_workgroup_size: 512
    .name:           _Z9hymba_fwd6Params
    .private_segment_fixed_size: 0
    .sgpr_count:     105
    .sgpr_spill_count: 0
    .symbol:         _Z9hymba_fwd6Params.kd
    .uniform_work_group_size: 1
    .uses_dynamic_stack: false
    .vgpr_count:     248
    .vgpr_spill_count: 0
    .wavefront_size: 64
